# in-proj and ffn-in epilogue stores made write-through (sc1) so the grid barrier's L2 writeback has less to flush; plus v24 changes
# speedup vs baseline: 1.0051x; 1.0051x over previous
; #define GAS __attribute__((address_space(1)))
; DI unsigned pk2(float lo, float hi) { f32x2 v = {lo, hi}; return __builtin_bit_cast(unsigned, __builtin_convertvector(v, bf2_t)); }
;     DI void operator()(AccRef acc, const Unit& u, int wr, int wc, int fr, int fq) const {
;     ...
;                     u32x4 w; w.x = pk2(v0[0], v0[1]); w.y = pk2(v0[2], v0[3]); w.z = pk2(v1[0], v1[1]); w.w = pk2(v1[2], v1[3]);
;                     if (cb >= 32 && cb < 44) {
;                         const int dsh = ((cb - 32) >> 2) * 2, t = row & (SEQ - 1), p = ((t & ((1 << dsh) - 1)) << (13 - dsh)) + (t >> dsh), ch = (c0 & 63) >> 3;
;                         *(GAS u32x4*)(PR + ((size_t)cb * NTOK + (size_t)(row - t)) * 64 + (size_t)(p >> 5) * 2048 + ((((ch >> 1) * 32 + (p & 31)) * 2 + (ch & 1)) * 8)) = w;
;                     } else
;                     *(GAS u32x4*)(PR + ((size_t)cb * NTOK + row) * 64 + (c0 & 63)) = w;
.LBB0_268:
	v_mov_b32_e32 v151, v0
	v_cvt_pk_bf16_f32 v126, v126, v127
	v_cvt_pk_bf16_f32 v127, v128, v129
	v_cvt_pk_bf16_f32 v128, v122, v123
	v_cvt_pk_bf16_f32 v129, v124, v125
	v_lshl_add_u64 v[122:123], v[150:151], 1, v[148:149]
	global_store_dwordx4 v[122:123], v[126:129], off sc1

; #define GAS __attribute__((address_space(1)))
; DI unsigned pk2(float lo, float hi) { f32x2 v = {lo, hi}; return __builtin_bit_cast(unsigned, __builtin_convertvector(v, bf2_t)); }
; DI float sigmoidf_(float x) { return __builtin_amdgcn_rcpf(1.f + fast_exp2(-x * LOG2E)); }
;     DI void operator()(AccRef acc, const Unit& u, int wr, int wc, int fr, int fq) const {
;     ...
;                     const float sc = (cb < 8 || (cb >= 20 && cb < 32)) ? C2 : 1.f; const bool sig = (cb == 56);
;                     const float f = rs * sc;
;                     f32x4 v0 = acc[ai][bj][m][0] * f, v1 = acc[ai][bj][m][1] * f;
;                     if (sig) { for (int i = 0; i < 4; ++i) { v0[i] = sigmoidf_(v0[i]); v1[i] = sigmoidf_(v1[i]); } }
;                     u32x4 w; w.x = pk2(v0[0], v0[1]); w.y = pk2(v0[2], v0[3]); w.z = pk2(v1[0], v1[1]); w.w = pk2(v1[2], v1[3]);
;                     if (cb >= 32 && cb < 44) {
;                         const int dsh = ((cb - 32) >> 2) * 2, t = row & (SEQ - 1), p = ((t & ((1 << dsh) - 1)) << (13 - dsh)) + (t >> dsh), ch = (c0 & 63) >> 3;
;                         *(GAS u32x4*)(PR + ((size_t)cb * NTOK + (size_t)(row - t)) * 64 + (size_t)(p >> 5) * 2048 + ((((ch >> 1) * 32 + (p & 31)) * 2 + (ch & 1)) * 8)) = w;
;                     } else
;                     *(GAS u32x4*)(PR + ((size_t)cb * NTOK + row) * 64 + (c0 & 63)) = w;
.LBB0_274:
	s_cmp_lt_i32 s28, 8
	s_cselect_b64 s[6:7], -1, 0
	s_sub_i32 s21, s28, 20
	s_cmp_lt_u32 s21, 12
	s_cselect_b64 s[50:51], -1, 0
	s_or_b64 vcc, s[6:7], s[50:51]
	v_cndmask_b32_e32 v125, 1.0, v220, vcc
	s_waitcnt lgkmcnt(0)
	v_mul_f32_e32 v128, v125, v157
	v_pk_mul_f32 v[146:147], v[116:117], v[128:129] op_sel_hi:[1,0]
	v_pk_mul_f32 v[116:117], v[114:115], v[128:129] op_sel_hi:[1,0]
	v_pk_mul_f32 v[120:121], v[120:121], v[128:129] op_sel_hi:[1,0]
	v_pk_mul_f32 v[114:115], v[118:119], v[128:129] op_sel_hi:[1,0]
	v_mov_b32_e32 v125, v0
	v_cvt_pk_bf16_f32 v114, v114, v115
	v_cvt_pk_bf16_f32 v115, v120, v121
	v_cvt_pk_bf16_f32 v116, v116, v117
	v_cvt_pk_bf16_f32 v117, v146, v147
	v_lshl_add_u64 v[118:119], v[124:125], 1, v[122:123]
	global_store_dwordx4 v[118:119], v[114:117], off sc1

; #define GAS __attribute__((address_space(1)))
; DI unsigned pk2(float lo, float hi) { f32x2 v = {lo, hi}; return __builtin_bit_cast(unsigned, __builtin_convertvector(v, bf2_t)); }
;     DI void operator()(AccRef acc, const Unit& u, int wr, int wc, int fr, int fq) const {
;     ...
;                     u32x4 w; w.x = pk2(v0[0], v0[1]); w.y = pk2(v0[2], v0[3]); w.z = pk2(v1[0], v1[1]); w.w = pk2(v1[2], v1[3]);
;                     if (cb >= 32 && cb < 44) {
;                         const int dsh = ((cb - 32) >> 2) * 2, t = row & (SEQ - 1), p = ((t & ((1 << dsh) - 1)) << (13 - dsh)) + (t >> dsh), ch = (c0 & 63) >> 3;
;                         *(GAS u32x4*)(PR + ((size_t)cb * NTOK + (size_t)(row - t)) * 64 + (size_t)(p >> 5) * 2048 + ((((ch >> 1) * 32 + (p & 31)) * 2 + (ch & 1)) * 8)) = w;
;                     } else
;                     *(GAS u32x4*)(PR + ((size_t)cb * NTOK + row) * 64 + (c0 & 63)) = w;
.LBB0_284:
	v_mov_b32_e32 v121, v0
	v_cvt_pk_bf16_f32 v110, v110, v111
	v_cvt_pk_bf16_f32 v111, v112, v113
	v_cvt_pk_bf16_f32 v112, v106, v107
	v_cvt_pk_bf16_f32 v113, v108, v109
	v_lshl_add_u64 v[106:107], v[120:121], 1, v[118:119]
	global_store_dwordx4 v[106:107], v[110:113], off sc1

; #define GAS __attribute__((address_space(1)))
; DI unsigned pk2(float lo, float hi) { f32x2 v = {lo, hi}; return __builtin_bit_cast(unsigned, __builtin_convertvector(v, bf2_t)); }
; DI float sigmoidf_(float x) { return __builtin_amdgcn_rcpf(1.f + fast_exp2(-x * LOG2E)); }
;     DI void operator()(AccRef acc, const Unit& u, int wr, int wc, int fr, int fq) const {
;     ...
;                     const float sc = (cb < 8 || (cb >= 20 && cb < 32)) ? C2 : 1.f; const bool sig = (cb == 56);
;                     const float f = rs * sc;
;                     f32x4 v0 = acc[ai][bj][m][0] * f, v1 = acc[ai][bj][m][1] * f;
;                     if (sig) { for (int i = 0; i < 4; ++i) { v0[i] = sigmoidf_(v0[i]); v1[i] = sigmoidf_(v1[i]); } }
;                     u32x4 w; w.x = pk2(v0[0], v0[1]); w.y = pk2(v0[2], v0[3]); w.z = pk2(v1[0], v1[1]); w.w = pk2(v1[2], v1[3]);
;                     if (cb >= 32 && cb < 44) {
;                         const int dsh = ((cb - 32) >> 2) * 2, t = row & (SEQ - 1), p = ((t & ((1 << dsh) - 1)) << (13 - dsh)) + (t >> dsh), ch = (c0 & 63) >> 3;
;                         *(GAS u32x4*)(PR + ((size_t)cb * NTOK + (size_t)(row - t)) * 64 + (size_t)(p >> 5) * 2048 + ((((ch >> 1) * 32 + (p & 31)) * 2 + (ch & 1)) * 8)) = w;
;                     } else
;                     *(GAS u32x4*)(PR + ((size_t)cb * NTOK + row) * 64 + (c0 & 63)) = w;
.LBB0_290:
	s_cmp_lt_i32 s28, 8
	s_cselect_b64 s[30:31], -1, 0
	s_sub_i32 s21, s28, 20
	s_cmp_lt_u32 s21, 12
	s_cselect_b64 s[50:51], -1, 0
	s_or_b64 vcc, s[30:31], s[50:51]
	v_cndmask_b32_e32 v109, 1.0, v220, vcc
	s_waitcnt lgkmcnt(0)
	v_mul_f32_e32 v110, v109, v122
	v_pk_mul_f32 v[112:113], v[100:101], v[110:111] op_sel_hi:[1,0]
	v_pk_mul_f32 v[100:101], v[98:99], v[110:111] op_sel_hi:[1,0]
	v_pk_mul_f32 v[104:105], v[104:105], v[110:111] op_sel_hi:[1,0]
	v_pk_mul_f32 v[98:99], v[102:103], v[110:111] op_sel_hi:[1,0]
	v_mov_b32_e32 v109, v0
	v_cvt_pk_bf16_f32 v98, v98, v99
	v_cvt_pk_bf16_f32 v99, v104, v105
	v_cvt_pk_bf16_f32 v100, v100, v101
	v_cvt_pk_bf16_f32 v101, v112, v113
	v_lshl_add_u64 v[102:103], v[108:109], 1, v[106:107]
	global_store_dwordx4 v[102:103], v[98:101], off sc1

; #define GAS __attribute__((address_space(1)))
; DI unsigned pk2(float lo, float hi) { f32x2 v = {lo, hi}; return __builtin_bit_cast(unsigned, __builtin_convertvector(v, bf2_t)); }
;     DI void operator()(AccRef acc, const Unit& u, int wr, int wc, int fr, int fq) const {
;     ...
;                     u32x4 w; w.x = pk2(v0[0], v0[1]); w.y = pk2(v0[2], v0[3]); w.z = pk2(v1[0], v1[1]); w.w = pk2(v1[2], v1[3]);
;                     if (cb >= 32 && cb < 44) {
;                         const int dsh = ((cb - 32) >> 2) * 2, t = row & (SEQ - 1), p = ((t & ((1 << dsh) - 1)) << (13 - dsh)) + (t >> dsh), ch = (c0 & 63) >> 3;
;                         *(GAS u32x4*)(PR + ((size_t)cb * NTOK + (size_t)(row - t)) * 64 + (size_t)(p >> 5) * 2048 + ((((ch >> 1) * 32 + (p & 31)) * 2 + (ch & 1)) * 8)) = w;
;                     } else
;                     *(GAS u32x4*)(PR + ((size_t)cb * NTOK + row) * 64 + (c0 & 63)) = w;
.LBB0_300:
	v_mov_b32_e32 v105, v0
	v_cvt_pk_bf16_f32 v94, v94, v95
	v_cvt_pk_bf16_f32 v95, v96, v97
	v_cvt_pk_bf16_f32 v96, v90, v91
	v_cvt_pk_bf16_f32 v97, v92, v93
	v_lshl_add_u64 v[90:91], v[104:105], 1, v[102:103]
	global_store_dwordx4 v[90:91], v[94:97], off sc1

; #define GAS __attribute__((address_space(1)))
; DI unsigned pk2(float lo, float hi) { f32x2 v = {lo, hi}; return __builtin_bit_cast(unsigned, __builtin_convertvector(v, bf2_t)); }
; DI float sigmoidf_(float x) { return __builtin_amdgcn_rcpf(1.f + fast_exp2(-x * LOG2E)); }
;     DI void operator()(AccRef acc, const Unit& u, int wr, int wc, int fr, int fq) const {
;     ...
;                     const float sc = (cb < 8 || (cb >= 20 && cb < 32)) ? C2 : 1.f; const bool sig = (cb == 56);
;                     const float f = rs * sc;
;                     f32x4 v0 = acc[ai][bj][m][0] * f, v1 = acc[ai][bj][m][1] * f;
;                     if (sig) { for (int i = 0; i < 4; ++i) { v0[i] = sigmoidf_(v0[i]); v1[i] = sigmoidf_(v1[i]); } }
;                     u32x4 w; w.x = pk2(v0[0], v0[1]); w.y = pk2(v0[2], v0[3]); w.z = pk2(v1[0], v1[1]); w.w = pk2(v1[2], v1[3]);
;                     if (cb >= 32 && cb < 44) {
;                         const int dsh = ((cb - 32) >> 2) * 2, t = row & (SEQ - 1), p = ((t & ((1 << dsh) - 1)) << (13 - dsh)) + (t >> dsh), ch = (c0 & 63) >> 3;
;                         *(GAS u32x4*)(PR + ((size_t)cb * NTOK + (size_t)(row - t)) * 64 + (size_t)(p >> 5) * 2048 + ((((ch >> 1) * 32 + (p & 31)) * 2 + (ch & 1)) * 8)) = w;
;                     } else
;                     *(GAS u32x4*)(PR + ((size_t)cb * NTOK + row) * 64 + (c0 & 63)) = w;
.LBB0_306:
	s_cmp_lt_i32 s28, 8
	s_cselect_b64 s[30:31], -1, 0
	s_sub_i32 s21, s28, 20
	s_cmp_lt_u32 s21, 12
	s_cselect_b64 s[50:51], -1, 0
	s_or_b64 vcc, s[30:31], s[50:51]
	v_cndmask_b32_e32 v93, 1.0, v220, vcc
	s_waitcnt lgkmcnt(0)
	v_mul_f32_e32 v94, v93, v106
	v_pk_mul_f32 v[96:97], v[84:85], v[94:95] op_sel_hi:[1,0]
	v_pk_mul_f32 v[84:85], v[82:83], v[94:95] op_sel_hi:[1,0]
	v_pk_mul_f32 v[88:89], v[88:89], v[94:95] op_sel_hi:[1,0]
	v_pk_mul_f32 v[82:83], v[86:87], v[94:95] op_sel_hi:[1,0]
	v_mov_b32_e32 v93, v0
	v_cvt_pk_bf16_f32 v82, v82, v83
	v_cvt_pk_bf16_f32 v83, v88, v89
	v_cvt_pk_bf16_f32 v84, v84, v85
	v_cvt_pk_bf16_f32 v85, v96, v97
	v_lshl_add_u64 v[86:87], v[92:93], 1, v[90:91]
	global_store_dwordx4 v[86:87], v[82:85], off sc1

; #define GAS __attribute__((address_space(1)))
; DI unsigned pk2(float lo, float hi) { f32x2 v = {lo, hi}; return __builtin_bit_cast(unsigned, __builtin_convertvector(v, bf2_t)); }
;     DI void operator()(AccRef acc, const Unit& u, int wr, int wc, int fr, int fq) const {
;     ...
;                     u32x4 w; w.x = pk2(v0[0], v0[1]); w.y = pk2(v0[2], v0[3]); w.z = pk2(v1[0], v1[1]); w.w = pk2(v1[2], v1[3]);
;                     if (cb >= 32 && cb < 44) {
;                         const int dsh = ((cb - 32) >> 2) * 2, t = row & (SEQ - 1), p = ((t & ((1 << dsh) - 1)) << (13 - dsh)) + (t >> dsh), ch = (c0 & 63) >> 3;
;                         *(GAS u32x4*)(PR + ((size_t)cb * NTOK + (size_t)(row - t)) * 64 + (size_t)(p >> 5) * 2048 + ((((ch >> 1) * 32 + (p & 31)) * 2 + (ch & 1)) * 8)) = w;
;                     } else
;                     *(GAS u32x4*)(PR + ((size_t)cb * NTOK + row) * 64 + (c0 & 63)) = w;
.LBB0_316:
	v_mov_b32_e32 v89, v0
	v_cvt_pk_bf16_f32 v78, v78, v79
	v_cvt_pk_bf16_f32 v79, v80, v81
	v_cvt_pk_bf16_f32 v80, v74, v75
	v_cvt_pk_bf16_f32 v81, v76, v77
	v_lshl_add_u64 v[74:75], v[88:89], 1, v[86:87]
	global_store_dwordx4 v[74:75], v[78:81], off sc1

; #define GAS __attribute__((address_space(1)))
; DI unsigned pk2(float lo, float hi) { f32x2 v = {lo, hi}; return __builtin_bit_cast(unsigned, __builtin_convertvector(v, bf2_t)); }
; DI float sigmoidf_(float x) { return __builtin_amdgcn_rcpf(1.f + fast_exp2(-x * LOG2E)); }
;     DI void operator()(AccRef acc, const Unit& u, int wr, int wc, int fr, int fq) const {
;     ...
;                     const float sc = (cb < 8 || (cb >= 20 && cb < 32)) ? C2 : 1.f; const bool sig = (cb == 56);
;                     const float f = rs * sc;
;                     f32x4 v0 = acc[ai][bj][m][0] * f, v1 = acc[ai][bj][m][1] * f;
;                     if (sig) { for (int i = 0; i < 4; ++i) { v0[i] = sigmoidf_(v0[i]); v1[i] = sigmoidf_(v1[i]); } }
;                     u32x4 w; w.x = pk2(v0[0], v0[1]); w.y = pk2(v0[2], v0[3]); w.z = pk2(v1[0], v1[1]); w.w = pk2(v1[2], v1[3]);
;                     if (cb >= 32 && cb < 44) {
;                         const int dsh = ((cb - 32) >> 2) * 2, t = row & (SEQ - 1), p = ((t & ((1 << dsh) - 1)) << (13 - dsh)) + (t >> dsh), ch = (c0 & 63) >> 3;
;                         *(GAS u32x4*)(PR + ((size_t)cb * NTOK + (size_t)(row - t)) * 64 + (size_t)(p >> 5) * 2048 + ((((ch >> 1) * 32 + (p & 31)) * 2 + (ch & 1)) * 8)) = w;
;                     } else
;                     *(GAS u32x4*)(PR + ((size_t)cb * NTOK + row) * 64 + (c0 & 63)) = w;
.LBB0_322:
	s_cmp_lt_i32 s28, 8
	s_cselect_b64 s[30:31], -1, 0
	s_sub_i32 s21, s28, 20
	s_cmp_lt_u32 s21, 12
	s_cselect_b64 s[50:51], -1, 0
	s_or_b64 vcc, s[30:31], s[50:51]
	v_cndmask_b32_e32 v77, 1.0, v220, vcc
	s_waitcnt lgkmcnt(0)
	v_mul_f32_e32 v78, v77, v90
	v_pk_mul_f32 v[80:81], v[68:69], v[78:79] op_sel_hi:[1,0]
	v_pk_mul_f32 v[68:69], v[66:67], v[78:79] op_sel_hi:[1,0]
	v_pk_mul_f32 v[72:73], v[72:73], v[78:79] op_sel_hi:[1,0]
	v_pk_mul_f32 v[66:67], v[70:71], v[78:79] op_sel_hi:[1,0]
	v_mov_b32_e32 v77, v0
	v_cvt_pk_bf16_f32 v66, v66, v67
	v_cvt_pk_bf16_f32 v67, v72, v73
	v_cvt_pk_bf16_f32 v68, v68, v69
	v_cvt_pk_bf16_f32 v69, v80, v81
	v_lshl_add_u64 v[70:71], v[76:77], 1, v[74:75]
	global_store_dwordx4 v[70:71], v[66:69], off sc1

; #define GAS __attribute__((address_space(1)))
; DI unsigned pk2(float lo, float hi) { f32x2 v = {lo, hi}; return __builtin_bit_cast(unsigned, __builtin_convertvector(v, bf2_t)); }
;     DI void operator()(AccRef acc, const Unit& u, int wr, int wc, int fr, int fq) const {
;     ...
;                     u32x4 w; w.x = pk2(v0[0], v0[1]); w.y = pk2(v0[2], v0[3]); w.z = pk2(v1[0], v1[1]); w.w = pk2(v1[2], v1[3]);
;                     if (cb >= 32 && cb < 44) {
;                         const int dsh = ((cb - 32) >> 2) * 2, t = row & (SEQ - 1), p = ((t & ((1 << dsh) - 1)) << (13 - dsh)) + (t >> dsh), ch = (c0 & 63) >> 3;
;                         *(GAS u32x4*)(PR + ((size_t)cb * NTOK + (size_t)(row - t)) * 64 + (size_t)(p >> 5) * 2048 + ((((ch >> 1) * 32 + (p & 31)) * 2 + (ch & 1)) * 8)) = w;
;                     } else
;                     *(GAS u32x4*)(PR + ((size_t)cb * NTOK + row) * 64 + (c0 & 63)) = w;
.LBB0_332:
	v_mov_b32_e32 v75, v0
	v_cvt_pk_bf16_f32 v62, v62, v63
	v_cvt_pk_bf16_f32 v63, v64, v65
	v_cvt_pk_bf16_f32 v64, v58, v59
	v_cvt_pk_bf16_f32 v65, v60, v61
	v_lshl_add_u64 v[58:59], v[74:75], 1, v[72:73]
	global_store_dwordx4 v[58:59], v[62:65], off sc1

; #define GAS __attribute__((address_space(1)))
; DI unsigned pk2(float lo, float hi) { f32x2 v = {lo, hi}; return __builtin_bit_cast(unsigned, __builtin_convertvector(v, bf2_t)); }
; DI float sigmoidf_(float x) { return __builtin_amdgcn_rcpf(1.f + fast_exp2(-x * LOG2E)); }
;     DI void operator()(AccRef acc, const Unit& u, int wr, int wc, int fr, int fq) const {
;     ...
;                     const float sc = (cb < 8 || (cb >= 20 && cb < 32)) ? C2 : 1.f; const bool sig = (cb == 56);
;                     const float f = rs * sc;
;                     f32x4 v0 = acc[ai][bj][m][0] * f, v1 = acc[ai][bj][m][1] * f;
;                     if (sig) { for (int i = 0; i < 4; ++i) { v0[i] = sigmoidf_(v0[i]); v1[i] = sigmoidf_(v1[i]); } }
;                     u32x4 w; w.x = pk2(v0[0], v0[1]); w.y = pk2(v0[2], v0[3]); w.z = pk2(v1[0], v1[1]); w.w = pk2(v1[2], v1[3]);
;                     if (cb >= 32 && cb < 44) {
;                         const int dsh = ((cb - 32) >> 2) * 2, t = row & (SEQ - 1), p = ((t & ((1 << dsh) - 1)) << (13 - dsh)) + (t >> dsh), ch = (c0 & 63) >> 3;
;                         *(GAS u32x4*)(PR + ((size_t)cb * NTOK + (size_t)(row - t)) * 64 + (size_t)(p >> 5) * 2048 + ((((ch >> 1) * 32 + (p & 31)) * 2 + (ch & 1)) * 8)) = w;
;                     } else
;                     *(GAS u32x4*)(PR + ((size_t)cb * NTOK + row) * 64 + (c0 & 63)) = w;
.LBB0_338:
	s_cmp_lt_i32 s28, 8
	s_cselect_b64 s[30:31], -1, 0
	s_sub_i32 s21, s28, 20
	s_cmp_lt_u32 s21, 12
	s_cselect_b64 s[50:51], -1, 0
	s_or_b64 vcc, s[30:31], s[50:51]
	v_cndmask_b32_e32 v61, 1.0, v220, vcc
	s_waitcnt lgkmcnt(0)
	v_mul_f32_e32 v62, v61, v76
	v_pk_mul_f32 v[64:65], v[52:53], v[62:63] op_sel_hi:[1,0]
	v_pk_mul_f32 v[52:53], v[50:51], v[62:63] op_sel_hi:[1,0]
	v_pk_mul_f32 v[56:57], v[56:57], v[62:63] op_sel_hi:[1,0]
	v_pk_mul_f32 v[50:51], v[54:55], v[62:63] op_sel_hi:[1,0]
	v_mov_b32_e32 v61, v0
	v_cvt_pk_bf16_f32 v50, v50, v51
	v_cvt_pk_bf16_f32 v51, v56, v57
	v_cvt_pk_bf16_f32 v52, v52, v53
	v_cvt_pk_bf16_f32 v53, v64, v65
	v_lshl_add_u64 v[54:55], v[60:61], 1, v[58:59]
	global_store_dwordx4 v[54:55], v[50:53], off sc1

; #define GAS __attribute__((address_space(1)))
; DI unsigned pk2(float lo, float hi) { f32x2 v = {lo, hi}; return __builtin_bit_cast(unsigned, __builtin_convertvector(v, bf2_t)); }
;     DI void operator()(AccRef acc, const Unit& u, int wr, int wc, int fr, int fq) const {
;     ...
;                     u32x4 w; w.x = pk2(v0[0], v0[1]); w.y = pk2(v0[2], v0[3]); w.z = pk2(v1[0], v1[1]); w.w = pk2(v1[2], v1[3]);
;                     if (cb >= 32 && cb < 44) {
;                         const int dsh = ((cb - 32) >> 2) * 2, t = row & (SEQ - 1), p = ((t & ((1 << dsh) - 1)) << (13 - dsh)) + (t >> dsh), ch = (c0 & 63) >> 3;
;                         *(GAS u32x4*)(PR + ((size_t)cb * NTOK + (size_t)(row - t)) * 64 + (size_t)(p >> 5) * 2048 + ((((ch >> 1) * 32 + (p & 31)) * 2 + (ch & 1)) * 8)) = w;
;                     } else
;                     *(GAS u32x4*)(PR + ((size_t)cb * NTOK + row) * 64 + (c0 & 63)) = w;
.LBB0_348:
	v_mov_b32_e32 v57, v0
	v_cvt_pk_bf16_f32 v46, v46, v47
	v_cvt_pk_bf16_f32 v47, v48, v49
	v_cvt_pk_bf16_f32 v48, v42, v43
	v_cvt_pk_bf16_f32 v49, v44, v45
	v_lshl_add_u64 v[42:43], v[56:57], 1, v[54:55]
	global_store_dwordx4 v[42:43], v[46:49], off sc1

; #define GAS __attribute__((address_space(1)))
; DI unsigned pk2(float lo, float hi) { f32x2 v = {lo, hi}; return __builtin_bit_cast(unsigned, __builtin_convertvector(v, bf2_t)); }
; DI float sigmoidf_(float x) { return __builtin_amdgcn_rcpf(1.f + fast_exp2(-x * LOG2E)); }
;     DI void operator()(AccRef acc, const Unit& u, int wr, int wc, int fr, int fq) const {
;     ...
;                     const float sc = (cb < 8 || (cb >= 20 && cb < 32)) ? C2 : 1.f; const bool sig = (cb == 56);
;                     const float f = rs * sc;
;                     f32x4 v0 = acc[ai][bj][m][0] * f, v1 = acc[ai][bj][m][1] * f;
;                     if (sig) { for (int i = 0; i < 4; ++i) { v0[i] = sigmoidf_(v0[i]); v1[i] = sigmoidf_(v1[i]); } }
;                     u32x4 w; w.x = pk2(v0[0], v0[1]); w.y = pk2(v0[2], v0[3]); w.z = pk2(v1[0], v1[1]); w.w = pk2(v1[2], v1[3]);
;                     if (cb >= 32 && cb < 44) {
;                         const int dsh = ((cb - 32) >> 2) * 2, t = row & (SEQ - 1), p = ((t & ((1 << dsh) - 1)) << (13 - dsh)) + (t >> dsh), ch = (c0 & 63) >> 3;
;                         *(GAS u32x4*)(PR + ((size_t)cb * NTOK + (size_t)(row - t)) * 64 + (size_t)(p >> 5) * 2048 + ((((ch >> 1) * 32 + (p & 31)) * 2 + (ch & 1)) * 8)) = w;
;                     } else
;                     *(GAS u32x4*)(PR + ((size_t)cb * NTOK + row) * 64 + (c0 & 63)) = w;
.LBB0_354:
	s_cmp_lt_i32 s28, 8
	s_cselect_b64 s[30:31], -1, 0
	s_sub_i32 s21, s28, 20
	s_cmp_lt_u32 s21, 12
	s_cselect_b64 s[50:51], -1, 0
	s_or_b64 vcc, s[30:31], s[50:51]
	v_cndmask_b32_e32 v45, 1.0, v220, vcc
	s_waitcnt lgkmcnt(0)
	v_mul_f32_e32 v46, v45, v58
	v_pk_mul_f32 v[48:49], v[36:37], v[46:47] op_sel_hi:[1,0]
	v_pk_mul_f32 v[36:37], v[34:35], v[46:47] op_sel_hi:[1,0]
	v_pk_mul_f32 v[40:41], v[40:41], v[46:47] op_sel_hi:[1,0]
	v_pk_mul_f32 v[34:35], v[38:39], v[46:47] op_sel_hi:[1,0]
	v_mov_b32_e32 v45, v0
	v_cvt_pk_bf16_f32 v34, v34, v35
	v_cvt_pk_bf16_f32 v35, v40, v41
	v_cvt_pk_bf16_f32 v36, v36, v37
	v_cvt_pk_bf16_f32 v37, v48, v49
	v_lshl_add_u64 v[38:39], v[44:45], 1, v[42:43]
	global_store_dwordx4 v[38:39], v[34:37], off sc1

; #define GAS __attribute__((address_space(1)))
; DI unsigned pk2(float lo, float hi) { f32x2 v = {lo, hi}; return __builtin_bit_cast(unsigned, __builtin_convertvector(v, bf2_t)); }
;     DI void operator()(AccRef acc, const Unit& u, int wr, int wc, int fr, int fq) const {
;     ...
;                     u32x4 w; w.x = pk2(v0[0], v0[1]); w.y = pk2(v0[2], v0[3]); w.z = pk2(v1[0], v1[1]); w.w = pk2(v1[2], v1[3]);
;                     if (cb >= 32 && cb < 44) {
;                         const int dsh = ((cb - 32) >> 2) * 2, t = row & (SEQ - 1), p = ((t & ((1 << dsh) - 1)) << (13 - dsh)) + (t >> dsh), ch = (c0 & 63) >> 3;
;                         *(GAS u32x4*)(PR + ((size_t)cb * NTOK + (size_t)(row - t)) * 64 + (size_t)(p >> 5) * 2048 + ((((ch >> 1) * 32 + (p & 31)) * 2 + (ch & 1)) * 8)) = w;
;                     } else
;                     *(GAS u32x4*)(PR + ((size_t)cb * NTOK + row) * 64 + (c0 & 63)) = w;
.LBB0_364:
	v_mov_b32_e32 v41, v0
	v_cvt_pk_bf16_f32 v30, v30, v31
	v_cvt_pk_bf16_f32 v31, v32, v33
	v_cvt_pk_bf16_f32 v32, v26, v27
	v_cvt_pk_bf16_f32 v33, v28, v29
	v_lshl_add_u64 v[26:27], v[40:41], 1, v[38:39]
	global_store_dwordx4 v[26:27], v[30:33], off sc1

; #define GAS __attribute__((address_space(1)))
; DI unsigned pk2(float lo, float hi) { f32x2 v = {lo, hi}; return __builtin_bit_cast(unsigned, __builtin_convertvector(v, bf2_t)); }
; DI float sigmoidf_(float x) { return __builtin_amdgcn_rcpf(1.f + fast_exp2(-x * LOG2E)); }
;     DI void operator()(AccRef acc, const Unit& u, int wr, int wc, int fr, int fq) const {
;     ...
;                     const float sc = (cb < 8 || (cb >= 20 && cb < 32)) ? C2 : 1.f; const bool sig = (cb == 56);
;                     const float f = rs * sc;
;                     f32x4 v0 = acc[ai][bj][m][0] * f, v1 = acc[ai][bj][m][1] * f;
;                     if (sig) { for (int i = 0; i < 4; ++i) { v0[i] = sigmoidf_(v0[i]); v1[i] = sigmoidf_(v1[i]); } }
;                     u32x4 w; w.x = pk2(v0[0], v0[1]); w.y = pk2(v0[2], v0[3]); w.z = pk2(v1[0], v1[1]); w.w = pk2(v1[2], v1[3]);
;                     if (cb >= 32 && cb < 44) {
;                         const int dsh = ((cb - 32) >> 2) * 2, t = row & (SEQ - 1), p = ((t & ((1 << dsh) - 1)) << (13 - dsh)) + (t >> dsh), ch = (c0 & 63) >> 3;
;                         *(GAS u32x4*)(PR + ((size_t)cb * NTOK + (size_t)(row - t)) * 64 + (size_t)(p >> 5) * 2048 + ((((ch >> 1) * 32 + (p & 31)) * 2 + (ch & 1)) * 8)) = w;
;                     } else
;                     *(GAS u32x4*)(PR + ((size_t)cb * NTOK + row) * 64 + (c0 & 63)) = w;
.LBB0_370:
	s_cmp_lt_i32 s28, 8
	s_cselect_b64 s[30:31], -1, 0
	s_sub_i32 s21, s28, 20
	s_cmp_lt_u32 s21, 12
	s_cselect_b64 s[50:51], -1, 0
	s_or_b64 vcc, s[30:31], s[50:51]
	v_cndmask_b32_e32 v29, 1.0, v220, vcc
	s_waitcnt lgkmcnt(0)
	v_mul_f32_e32 v30, v29, v42
	v_pk_mul_f32 v[32:33], v[20:21], v[30:31] op_sel_hi:[1,0]
	v_pk_mul_f32 v[20:21], v[18:19], v[30:31] op_sel_hi:[1,0]
	v_pk_mul_f32 v[24:25], v[24:25], v[30:31] op_sel_hi:[1,0]
	v_pk_mul_f32 v[18:19], v[22:23], v[30:31] op_sel_hi:[1,0]
	v_mov_b32_e32 v29, v0
	v_cvt_pk_bf16_f32 v18, v18, v19
	v_cvt_pk_bf16_f32 v19, v24, v25
	v_cvt_pk_bf16_f32 v20, v20, v21
	v_cvt_pk_bf16_f32 v21, v32, v33
	v_lshl_add_u64 v[22:23], v[28:29], 1, v[26:27]
	global_store_dwordx4 v[22:23], v[18:21], off sc1

; #define GAS __attribute__((address_space(1)))
; DI unsigned pk2(float lo, float hi) { f32x2 v = {lo, hi}; return __builtin_bit_cast(unsigned, __builtin_convertvector(v, bf2_t)); }
; DI float sigmoidf_(float x) { return __builtin_amdgcn_rcpf(1.f + fast_exp2(-x * LOG2E)); }
;     DI void operator()(AccRef acc, const Unit& u, int wr, int wc, int fr, int fq) const {
;     ...
;                     const float sc = (cb < 8 || (cb >= 20 && cb < 32)) ? C2 : 1.f; const bool sig = (cb == 56);
;                     const float f = rs * sc;
;                     f32x4 v0 = acc[ai][bj][m][0] * f, v1 = acc[ai][bj][m][1] * f;
;                     if (sig) { for (int i = 0; i < 4; ++i) { v0[i] = sigmoidf_(v0[i]); v1[i] = sigmoidf_(v1[i]); } }
;                     u32x4 w; w.x = pk2(v0[0], v0[1]); w.y = pk2(v0[2], v0[3]); w.z = pk2(v1[0], v1[1]); w.w = pk2(v1[2], v1[3]);
;                     if (cb >= 32 && cb < 44) {
;                         const int dsh = ((cb - 32) >> 2) * 2, t = row & (SEQ - 1), p = ((t & ((1 << dsh) - 1)) << (13 - dsh)) + (t >> dsh), ch = (c0 & 63) >> 3;
;                         *(GAS u32x4*)(PR + ((size_t)cb * NTOK + (size_t)(row - t)) * 64 + (size_t)(p >> 5) * 2048 + ((((ch >> 1) * 32 + (p & 31)) * 2 + (ch & 1)) * 8)) = w;
;                     } else
;                     *(GAS u32x4*)(PR + ((size_t)cb * NTOK + row) * 64 + (c0 & 63)) = w;
.LBB0_379:
	s_cmp_lt_i32 s28, 8
	s_cselect_b64 s[6:7], -1, 0
	s_sub_i32 s8, s28, 20
	s_cmp_lt_u32 s8, 12
	s_cselect_b64 s[8:9], -1, 0
	s_or_b64 vcc, s[6:7], s[8:9]
	v_cndmask_b32_e32 v13, 1.0, v220, vcc
	s_waitcnt lgkmcnt(0)
	v_mul_f32_e32 v14, v13, v26
	v_pk_mul_f32 v[16:17], v[4:5], v[14:15] op_sel_hi:[1,0]
	v_pk_mul_f32 v[4:5], v[2:3], v[14:15] op_sel_hi:[1,0]
	v_pk_mul_f32 v[8:9], v[8:9], v[14:15] op_sel_hi:[1,0]
	v_pk_mul_f32 v[2:3], v[6:7], v[14:15] op_sel_hi:[1,0]
	v_mov_b32_e32 v13, v0
	v_cvt_pk_bf16_f32 v2, v2, v3
	v_cvt_pk_bf16_f32 v3, v8, v9
	v_cvt_pk_bf16_f32 v4, v4, v5
	v_cvt_pk_bf16_f32 v5, v16, v17
	v_lshl_add_u64 v[6:7], v[12:13], 1, v[10:11]
	global_store_dwordx4 v[6:7], v[2:5], off sc1
	s_andn2_b64 vcc, exec, s[4:5]
	s_mov_b64 s[4:5], -1
	s_cbranch_vccnz .LBB0_250
	s_branch .LBB0_388

; #define GAS __attribute__((address_space(1)))
; DI unsigned pk2(float lo, float hi) { f32x2 v = {lo, hi}; return __builtin_bit_cast(unsigned, __builtin_convertvector(v, bf2_t)); }
;     DI void operator()(AccRef acc, const Unit& u, int wr, int wc, int fr, int fq) const {
;     ...
;                     u32x4 w; w.x = pk2(v0[0], v0[1]); w.y = pk2(v0[2], v0[3]); w.z = pk2(v1[0], v1[1]); w.w = pk2(v1[2], v1[3]);
;                     if (cb >= 32 && cb < 44) {
;                         const int dsh = ((cb - 32) >> 2) * 2, t = row & (SEQ - 1), p = ((t & ((1 << dsh) - 1)) << (13 - dsh)) + (t >> dsh), ch = (c0 & 63) >> 3;
;                         *(GAS u32x4*)(PR + ((size_t)cb * NTOK + (size_t)(row - t)) * 64 + (size_t)(p >> 5) * 2048 + ((((ch >> 1) * 32 + (p & 31)) * 2 + (ch & 1)) * 8)) = w;
;                     } else
;                     *(GAS u32x4*)(PR + ((size_t)cb * NTOK + row) * 64 + (c0 & 63)) = w;
.LBB0_386:
	v_mov_b32_e32 v25, v0
	v_cvt_pk_bf16_f32 v14, v14, v15
	v_cvt_pk_bf16_f32 v15, v16, v17
	v_cvt_pk_bf16_f32 v16, v10, v11
	v_cvt_pk_bf16_f32 v17, v12, v13
	v_lshl_add_u64 v[10:11], v[24:25], 1, v[22:23]
	global_store_dwordx4 v[10:11], v[14:17], off sc1
	s_and_b64 vcc, exec, s[8:9]
	s_cbranch_vccz .LBB0_375

; #define GAS __attribute__((address_space(1)))
; DI unsigned pk2(float lo, float hi) { f32x2 v = {lo, hi}; return __builtin_bit_cast(unsigned, __builtin_convertvector(v, bf2_t)); }
; DI float siluf_(float x) { return x * sigmoidf_(x); }
;     DI void operator()(AccRef acc, const Unit& u, int wr, int wc, int fr, int fq) const {
;         const int row0 = u.pm * 256 + wr * 64 + fr; const int c0 = u.pn * 128 + wc * 32 + 8 * fq;
;         unit_rs_table(rsum, u.pm, rsl);
; #pragma unroll
;         for (int ai = 0; ai < 2; ++ai)
; #pragma unroll
;             for (int m = 0; m < 4; ++m) {
;                 const int row = row0 + ai * 128 + m * 16; const float f = rsl[row - u.pm * 256];
;                 float o[8];
; #pragma unroll
;                 for (int i = 0; i < 8; ++i) { const float gt = acc[ai][0][m][i >> 2][i & 3] * f, up = acc[ai][1][m][i >> 2][i & 3] * f; o[i] = siluf_(gt) * up; }
;                 u32x4 w; w.x = pk2(o[0], o[1]); w.y = pk2(o[2], o[3]); w.z = pk2(o[4], o[5]); w.w = pk2(o[6], o[7]);
;                 *(GAS u32x4*)(ACT + (size_t)row * DFF + c0) = w;
;             }
.LBB0_1359:
	s_or_b64 exec, exec, s[20:21]
	s_waitcnt lgkmcnt(0)
	s_barrier
	ds_read_b32 v144, v146
	v_add_u32_e32 v149, s13, v1
	v_or_b32_e32 v153, 32, v149
	v_or_b32_e32 v151, 16, v149
	v_readlane_b32 s15, v254, 3
	v_subrev_u32_e32 v150, s13, v153
	v_or_b32_e32 v155, 48, v149
	v_subrev_u32_e32 v143, s13, v151
	v_lshl_add_u32 v152, v150, 2, s15
	v_subrev_u32_e32 v150, s13, v155
	v_lshl_add_u32 v143, v143, 2, s15
	v_lshl_add_u32 v154, v150, 2, s15
	s_waitcnt lgkmcnt(0)
	v_pk_mul_f32 v[126:127], v[126:127], v[144:145] op_sel_hi:[1,0]
	ds_read_b32 v150, v143
	ds_read_b32 v152, v152
	ds_read_b32 v154, v154
	v_mul_f32_e32 v143, 0xbfb8aa3b, v126
	v_mul_f32_e32 v157, 0xbfb8aa3b, v127
	v_pk_mul_f32 v[128:129], v[128:129], v[144:145] op_sel_hi:[1,0]
	v_exp_f32_e32 v156, v143
	v_exp_f32_e32 v157, v157
	v_mul_f32_e32 v158, 0xbfb8aa3b, v128
	v_mul_f32_e32 v159, 0xbfb8aa3b, v129
	v_exp_f32_e32 v158, v158
	v_exp_f32_e32 v159, v159
	v_add_f32_e32 v156, 1.0, v156
	v_add_f32_e32 v157, 1.0, v157
	v_rcp_f32_e32 v156, v156
	v_rcp_f32_e32 v157, v157
	v_add_f32_e32 v158, 1.0, v158
	v_add_f32_e32 v159, 1.0, v159
	v_rcp_f32_e32 v158, v158
	v_rcp_f32_e32 v159, v159
	v_pk_mul_f32 v[118:119], v[118:119], v[144:145] op_sel_hi:[1,0]
	v_pk_mul_f32 v[126:127], v[126:127], v[156:157]
	v_pk_mul_f32 v[122:123], v[122:123], v[144:145] op_sel_hi:[1,0]
	v_pk_mul_f32 v[118:119], v[118:119], v[126:127]
	v_pk_mul_f32 v[126:127], v[128:129], v[158:159]
	v_mul_f32_e32 v128, 0xbfb8aa3b, v122
	v_exp_f32_e32 v128, v128
	v_pk_mul_f32 v[120:121], v[120:121], v[144:145] op_sel_hi:[1,0]
	v_pk_mul_f32 v[124:125], v[124:125], v[144:145] op_sel_hi:[1,0]
	v_pk_mul_f32 v[120:121], v[120:121], v[126:127]
	v_mul_f32_e32 v126, 0xbfb8aa3b, v123
	v_exp_f32_e32 v127, v126
	v_add_f32_e32 v126, 1.0, v128
	v_mul_f32_e32 v128, 0xbfb8aa3b, v124
	v_mul_f32_e32 v129, 0xbfb8aa3b, v125
	v_exp_f32_e32 v128, v128
	v_exp_f32_e32 v129, v129
	v_add_f32_e32 v127, 1.0, v127
	v_rcp_f32_e32 v126, v126
	v_rcp_f32_e32 v127, v127
	v_add_f32_e32 v128, 1.0, v128
	v_add_f32_e32 v129, 1.0, v129
	v_rcp_f32_e32 v128, v128
	v_rcp_f32_e32 v129, v129
	v_pk_mul_f32 v[110:111], v[110:111], v[144:145] op_sel_hi:[1,0]
	v_pk_mul_f32 v[122:123], v[122:123], v[126:127]
	v_lshl_or_b32 v142, s44, 7, v147
	v_pk_mul_f32 v[110:111], v[110:111], v[122:123]
	v_pk_mul_f32 v[112:113], v[112:113], v[144:145] op_sel_hi:[1,0]
	v_pk_mul_f32 v[122:123], v[124:125], v[128:129]
	v_ashrrev_i32_e32 v143, 31, v142
	v_pk_mul_f32 v[112:113], v[112:113], v[122:123]
	v_cvt_pk_bf16_f32 v118, v118, v119
	v_cvt_pk_bf16_f32 v119, v120, v121
	v_cvt_pk_bf16_f32 v120, v110, v111
	v_mov_b64_e32 v[110:111], s[8:9]
	s_movk_i32 s13, 0x1600
	v_cvt_pk_bf16_f32 v121, v112, v113
	v_mad_i64_i32 v[122:123], s[20:21], v149, s13, v[110:111]
	v_lshlrev_b64 v[112:113], 1, v[142:143]
	v_lshl_add_u64 v[122:123], v[122:123], 0, v[112:113]
	s_waitcnt lgkmcnt(0)
	v_pk_mul_f32 v[114:115], v[114:115], v[150:151] op_sel_hi:[1,0]
	global_store_dwordx4 v[122:123], v[118:121], off sc1
	v_mul_f32_e32 v124, 0xbfb8aa3b, v114
	v_pk_mul_f32 v[116:117], v[116:117], v[150:151] op_sel_hi:[1,0]
	v_mul_f32_e32 v118, 0xbfb8aa3b, v115
	v_exp_f32_e32 v124, v124
	v_exp_f32_e32 v119, v118
	v_mul_f32_e32 v120, 0xbfb8aa3b, v116
	v_mul_f32_e32 v121, 0xbfb8aa3b, v117
	v_exp_f32_e32 v120, v120
	v_exp_f32_e32 v121, v121
	v_add_f32_e32 v118, 1.0, v124
	v_add_f32_e32 v119, 1.0, v119
	v_rcp_f32_e32 v118, v118
	v_rcp_f32_e32 v119, v119
	v_add_f32_e32 v120, 1.0, v120
	v_add_f32_e32 v121, 1.0, v121
	v_rcp_f32_e32 v120, v120
	v_rcp_f32_e32 v121, v121
	v_pk_mul_f32 v[102:103], v[102:103], v[150:151] op_sel_hi:[1,0]
	v_pk_mul_f32 v[114:115], v[114:115], v[118:119]
	v_pk_mul_f32 v[106:107], v[106:107], v[150:151] op_sel_hi:[1,0]
	v_pk_mul_f32 v[102:103], v[102:103], v[114:115]
	v_pk_mul_f32 v[114:115], v[116:117], v[120:121]
	v_mul_f32_e32 v116, 0xbfb8aa3b, v106
	v_exp_f32_e32 v116, v116
	v_pk_mul_f32 v[104:105], v[104:105], v[150:151] op_sel_hi:[1,0]
	v_pk_mul_f32 v[108:109], v[108:109], v[150:151] op_sel_hi:[1,0]
	v_pk_mul_f32 v[104:105], v[104:105], v[114:115]
	v_mul_f32_e32 v114, 0xbfb8aa3b, v107
	v_exp_f32_e32 v115, v114
	v_add_f32_e32 v114, 1.0, v116
	v_mul_f32_e32 v116, 0xbfb8aa3b, v108
	v_mul_f32_e32 v117, 0xbfb8aa3b, v109
	v_exp_f32_e32 v116, v116
	v_exp_f32_e32 v117, v117
	v_add_f32_e32 v115, 1.0, v115
	v_rcp_f32_e32 v114, v114
	v_rcp_f32_e32 v115, v115
	v_add_f32_e32 v116, 1.0, v116
	v_add_f32_e32 v117, 1.0, v117
	v_rcp_f32_e32 v116, v116
	v_rcp_f32_e32 v117, v117
	v_pk_mul_f32 v[94:95], v[94:95], v[150:151] op_sel_hi:[1,0]
	v_pk_mul_f32 v[106:107], v[106:107], v[114:115]
	v_pk_mul_f32 v[98:99], v[98:99], v[152:153] op_sel_hi:[1,0]
	v_pk_mul_f32 v[106:107], v[94:95], v[106:107]
	v_pk_mul_f32 v[94:95], v[96:97], v[150:151] op_sel_hi:[1,0]
	v_pk_mul_f32 v[96:97], v[108:109], v[116:117]
	v_pk_mul_f32 v[86:87], v[86:87], v[152:153] op_sel_hi:[1,0]
	v_pk_mul_f32 v[108:109], v[94:95], v[96:97]
	v_cvt_pk_bf16_f32 v94, v102, v103
	v_mad_i64_i32 v[102:103], s[20:21], v151, s13, v[110:111]
	v_cvt_pk_bf16_f32 v95, v104, v105
	v_cvt_pk_bf16_f32 v96, v106, v107
	v_cvt_pk_bf16_f32 v97, v108, v109
	v_lshl_add_u64 v[102:103], v[102:103], 0, v[112:113]
	v_mul_f32_e32 v104, 0xbfb8aa3b, v98
	global_store_dwordx4 v[102:103], v[94:97], off sc1
	v_exp_f32_e32 v104, v104
	v_pk_mul_f32 v[90:91], v[90:91], v[152:153] op_sel_hi:[1,0]
	v_mul_f32_e32 v94, 0xbfb8aa3b, v99
	v_pk_mul_f32 v[96:97], v[100:101], v[152:153] op_sel_hi:[1,0]
	v_exp_f32_e32 v95, v94
	v_mul_f32_e32 v100, 0xbfb8aa3b, v96
	v_mul_f32_e32 v101, 0xbfb8aa3b, v97
	v_exp_f32_e32 v100, v100
	v_exp_f32_e32 v101, v101
	v_add_f32_e32 v94, 1.0, v104
	v_add_f32_e32 v95, 1.0, v95
; #define GAS __attribute__((address_space(1)))
; DI unsigned pk2(float lo, float hi) { f32x2 v = {lo, hi}; return __builtin_bit_cast(unsigned, __builtin_convertvector(v, bf2_t)); }
; DI float siluf_(float x) { return x * sigmoidf_(x); }
;     DI void operator()(AccRef acc, const Unit& u, int wr, int wc, int fr, int fq) const {
;         const int row0 = u.pm * 256 + wr * 64 + fr; const int c0 = u.pn * 128 + wc * 32 + 8 * fq;
;         unit_rs_table(rsum, u.pm, rsl);
; #pragma unroll
;         for (int ai = 0; ai < 2; ++ai)
; #pragma unroll
;             for (int m = 0; m < 4; ++m) {
;                 const int row = row0 + ai * 128 + m * 16; const float f = rsl[row - u.pm * 256];
;                 float o[8];
; #pragma unroll
;                 for (int i = 0; i < 8; ++i) { const float gt = acc[ai][0][m][i >> 2][i & 3] * f, up = acc[ai][1][m][i >> 2][i & 3] * f; o[i] = siluf_(gt) * up; }
;                 u32x4 w; w.x = pk2(o[0], o[1]); w.y = pk2(o[2], o[3]); w.z = pk2(o[4], o[5]); w.w = pk2(o[6], o[7]);
;                 *(GAS u32x4*)(ACT + (size_t)row * DFF + c0) = w;
;             }
	v_rcp_f32_e32 v94, v94
	v_rcp_f32_e32 v95, v95
	v_add_f32_e32 v100, 1.0, v100
	v_add_f32_e32 v101, 1.0, v101
	v_rcp_f32_e32 v100, v100
	v_rcp_f32_e32 v101, v101
	v_pk_mul_f32 v[94:95], v[98:99], v[94:95]
	v_pk_mul_f32 v[88:89], v[88:89], v[152:153] op_sel_hi:[1,0]
	v_pk_mul_f32 v[86:87], v[86:87], v[94:95]
	v_pk_mul_f32 v[94:95], v[96:97], v[100:101]
	v_mul_f32_e32 v96, 0xbfb8aa3b, v90
	v_exp_f32_e32 v96, v96
	v_pk_mul_f32 v[88:89], v[88:89], v[94:95]
	v_mul_f32_e32 v94, 0xbfb8aa3b, v91
	v_pk_mul_f32 v[92:93], v[92:93], v[152:153] op_sel_hi:[1,0]
	v_exp_f32_e32 v95, v94
	v_add_f32_e32 v94, 1.0, v96
	v_mul_f32_e32 v96, 0xbfb8aa3b, v92
	v_mul_f32_e32 v97, 0xbfb8aa3b, v93
	v_exp_f32_e32 v96, v96
	v_exp_f32_e32 v97, v97
	v_add_f32_e32 v95, 1.0, v95
	v_rcp_f32_e32 v94, v94
	v_rcp_f32_e32 v95, v95
	v_add_f32_e32 v96, 1.0, v96
	v_add_f32_e32 v97, 1.0, v97
	v_rcp_f32_e32 v96, v96
	v_rcp_f32_e32 v97, v97
	v_pk_mul_f32 v[82:83], v[82:83], v[152:153] op_sel_hi:[1,0]
	v_pk_mul_f32 v[90:91], v[90:91], v[94:95]
	v_pk_mul_f32 v[78:79], v[78:79], v[154:155] op_sel_hi:[1,0]
	v_pk_mul_f32 v[90:91], v[82:83], v[90:91]
	v_pk_mul_f32 v[82:83], v[84:85], v[152:153] op_sel_hi:[1,0]
	v_pk_mul_f32 v[84:85], v[92:93], v[96:97]
	v_pk_mul_f32 v[80:81], v[80:81], v[154:155] op_sel_hi:[1,0]
	v_pk_mul_f32 v[92:93], v[82:83], v[84:85]
	v_cvt_pk_bf16_f32 v82, v86, v87
	v_mad_i64_i32 v[86:87], s[20:21], v153, s13, v[110:111]
	v_cvt_pk_bf16_f32 v83, v88, v89
	v_cvt_pk_bf16_f32 v84, v90, v91
	v_cvt_pk_bf16_f32 v85, v92, v93
	v_lshl_add_u64 v[86:87], v[86:87], 0, v[112:113]
	v_mul_f32_e32 v88, 0xbfb8aa3b, v78
	global_store_dwordx4 v[86:87], v[82:85], off sc1
	v_exp_f32_e32 v88, v88
	v_pk_mul_f32 v[70:71], v[70:71], v[154:155] op_sel_hi:[1,0]
	v_mul_f32_e32 v82, 0xbfb8aa3b, v79
	v_exp_f32_e32 v83, v82
	v_mul_f32_e32 v84, 0xbfb8aa3b, v80
	v_mul_f32_e32 v85, 0xbfb8aa3b, v81
	v_exp_f32_e32 v84, v84
	v_exp_f32_e32 v85, v85
	v_add_f32_e32 v82, 1.0, v88
	v_add_f32_e32 v83, 1.0, v83
	v_rcp_f32_e32 v82, v82
	v_rcp_f32_e32 v83, v83
	v_add_f32_e32 v84, 1.0, v84
	v_add_f32_e32 v85, 1.0, v85
	v_rcp_f32_e32 v84, v84
	v_rcp_f32_e32 v85, v85
	v_pk_mul_f32 v[78:79], v[78:79], v[82:83]
	v_pk_mul_f32 v[74:75], v[74:75], v[154:155] op_sel_hi:[1,0]
	v_pk_mul_f32 v[70:71], v[70:71], v[78:79]
	v_pk_mul_f32 v[78:79], v[80:81], v[84:85]
	v_mul_f32_e32 v80, 0xbfb8aa3b, v74
	v_exp_f32_e32 v80, v80
	v_pk_mul_f32 v[72:73], v[72:73], v[154:155] op_sel_hi:[1,0]
	v_pk_mul_f32 v[76:77], v[76:77], v[154:155] op_sel_hi:[1,0]
	v_pk_mul_f32 v[72:73], v[72:73], v[78:79]
	v_mul_f32_e32 v78, 0xbfb8aa3b, v75
	v_exp_f32_e32 v79, v78
	v_add_f32_e32 v78, 1.0, v80
	v_mul_f32_e32 v80, 0xbfb8aa3b, v76
	v_mul_f32_e32 v81, 0xbfb8aa3b, v77
	v_exp_f32_e32 v80, v80
	v_exp_f32_e32 v81, v81
	v_add_f32_e32 v79, 1.0, v79
	v_rcp_f32_e32 v78, v78
	v_rcp_f32_e32 v79, v79
	v_add_f32_e32 v80, 1.0, v80
	v_add_f32_e32 v81, 1.0, v81
	v_rcp_f32_e32 v80, v80
	v_rcp_f32_e32 v81, v81
	v_pk_mul_f32 v[66:67], v[66:67], v[154:155] op_sel_hi:[1,0]
	v_pk_mul_f32 v[74:75], v[74:75], v[78:79]
	s_andn2_b64 vcc, exec, s[4:5]
	v_pk_mul_f32 v[74:75], v[66:67], v[74:75]
	v_pk_mul_f32 v[66:67], v[68:69], v[154:155] op_sel_hi:[1,0]
	v_pk_mul_f32 v[68:69], v[76:77], v[80:81]
	s_mov_b64 s[4:5], -1
	v_pk_mul_f32 v[76:77], v[66:67], v[68:69]
	v_cvt_pk_bf16_f32 v68, v74, v75
	v_lshl_add_u32 v74, v1, 2, s15
	v_cvt_pk_bf16_f32 v66, v70, v71
	ds_read2_b32 v[70:71], v74 offset0:128 offset1:144
	v_cvt_pk_bf16_f32 v67, v72, v73
	v_mad_i64_i32 v[72:73], s[20:21], v155, s13, v[110:111]
	v_cvt_pk_bf16_f32 v69, v76, v77
	v_lshl_add_u64 v[72:73], v[72:73], 0, v[112:113]
	s_waitcnt lgkmcnt(0)
	v_pk_mul_f32 v[62:63], v[62:63], v[70:71] op_sel_hi:[1,0]
	global_store_dwordx4 v[72:73], v[66:69], off sc1
	v_pk_mul_f32 v[64:65], v[64:65], v[70:71] op_sel_hi:[1,0]
	v_pk_mul_f32 v[54:55], v[54:55], v[70:71] op_sel_hi:[1,0]
	v_mul_f32_e32 v66, 0xbfb8aa3b, v62
	v_mul_f32_e32 v67, 0xbfb8aa3b, v63
	v_exp_f32_e32 v66, v66
	v_exp_f32_e32 v67, v67
	v_mul_f32_e32 v68, 0xbfb8aa3b, v64
	v_mul_f32_e32 v69, 0xbfb8aa3b, v65
	v_exp_f32_e32 v68, v68
	v_exp_f32_e32 v69, v69
	v_add_f32_e32 v66, 1.0, v66
	v_add_f32_e32 v67, 1.0, v67
	v_rcp_f32_e32 v66, v66
	v_rcp_f32_e32 v67, v67
	v_add_f32_e32 v68, 1.0, v68
	v_add_f32_e32 v69, 1.0, v69
	v_rcp_f32_e32 v68, v68
	v_rcp_f32_e32 v69, v69
	v_pk_mul_f32 v[62:63], v[62:63], v[66:67]
	v_pk_mul_f32 v[58:59], v[58:59], v[70:71] op_sel_hi:[1,0]
	v_pk_mul_f32 v[54:55], v[54:55], v[62:63]
	v_pk_mul_f32 v[62:63], v[64:65], v[68:69]
	v_mul_f32_e32 v64, 0xbfb8aa3b, v58
	v_exp_f32_e32 v64, v64
	v_pk_mul_f32 v[56:57], v[56:57], v[70:71] op_sel_hi:[1,0]
	v_pk_mul_f32 v[60:61], v[60:61], v[70:71] op_sel_hi:[1,0]
	v_pk_mul_f32 v[56:57], v[56:57], v[62:63]
	v_mul_f32_e32 v62, 0xbfb8aa3b, v59
	v_exp_f32_e32 v63, v62
	v_add_f32_e32 v62, 1.0, v64
	v_mul_f32_e32 v64, 0xbfb8aa3b, v60
	v_mul_f32_e32 v65, 0xbfb8aa3b, v61
	v_exp_f32_e32 v64, v64
	v_exp_f32_e32 v65, v65
	v_add_f32_e32 v63, 1.0, v63
	v_rcp_f32_e32 v62, v62
	v_rcp_f32_e32 v63, v63
	v_add_f32_e32 v64, 1.0, v64
	v_add_f32_e32 v65, 1.0, v65
	v_rcp_f32_e32 v64, v64
	v_rcp_f32_e32 v65, v65
	v_pk_mul_f32 v[50:51], v[50:51], v[70:71] op_sel_hi:[1,0]
	v_pk_mul_f32 v[58:59], v[58:59], v[62:63]
	v_add_u32_e32 v72, 0x80, v149
	v_pk_mul_f32 v[58:59], v[50:51], v[58:59]
	v_pk_mul_f32 v[50:51], v[52:53], v[70:71] op_sel_hi:[1,0]
	v_pk_mul_f32 v[52:53], v[60:61], v[64:65]
	s_nop 0
	v_pk_mul_f32 v[60:61], v[50:51], v[52:53]
	v_cvt_pk_bf16_f32 v50, v54, v55
	v_mad_i64_i32 v[54:55], s[20:21], v72, s13, v[110:111]
	v_cvt_pk_bf16_f32 v51, v56, v57
	v_cvt_pk_bf16_f32 v52, v58, v59
	v_cvt_pk_bf16_f32 v53, v60, v61
; #define GAS __attribute__((address_space(1)))
; DI unsigned pk2(float lo, float hi) { f32x2 v = {lo, hi}; return __builtin_bit_cast(unsigned, __builtin_convertvector(v, bf2_t)); }
; DI float siluf_(float x) { return x * sigmoidf_(x); }
;     DI void operator()(AccRef acc, const Unit& u, int wr, int wc, int fr, int fq) const {
;         const int row0 = u.pm * 256 + wr * 64 + fr; const int c0 = u.pn * 128 + wc * 32 + 8 * fq;
;         unit_rs_table(rsum, u.pm, rsl);
; #pragma unroll
;         for (int ai = 0; ai < 2; ++ai)
; #pragma unroll
;             for (int m = 0; m < 4; ++m) {
;                 const int row = row0 + ai * 128 + m * 16; const float f = rsl[row - u.pm * 256];
;                 float o[8];
; #pragma unroll
;                 for (int i = 0; i < 8; ++i) { const float gt = acc[ai][0][m][i >> 2][i & 3] * f, up = acc[ai][1][m][i >> 2][i & 3] * f; o[i] = siluf_(gt) * up; }
;                 u32x4 w; w.x = pk2(o[0], o[1]); w.y = pk2(o[2], o[3]); w.z = pk2(o[4], o[5]); w.w = pk2(o[6], o[7]);
;                 *(GAS u32x4*)(ACT + (size_t)row * DFF + c0) = w;
;             }
	v_lshl_add_u64 v[54:55], v[54:55], 0, v[112:113]
	global_store_dwordx4 v[54:55], v[50:53], off sc1
	v_add_u32_e32 v56, 0x90, v149
	s_nop 0
	v_mov_b32_e32 v50, v71
	v_pk_mul_f32 v[46:47], v[46:47], v[50:51] op_sel_hi:[1,0]
	s_nop 0
	v_mul_f32_e32 v51, 0xbfb8aa3b, v46
	v_exp_f32_e32 v51, v51
	v_mul_f32_e32 v52, 0xbfb8aa3b, v47
	v_exp_f32_e32 v53, v52
	v_add_f32_e32 v51, 1.0, v51
	v_rcp_f32_e32 v52, v51
	v_pk_mul_f32 v[38:39], v[38:39], v[50:51] op_sel_hi:[1,0]
	v_add_f32_e32 v51, 1.0, v53
	v_pk_mul_f32 v[48:49], v[48:49], v[50:51] op_sel_hi:[1,0]
	s_nop 0
	v_mul_f32_e32 v53, 0xbfb8aa3b, v48
	v_exp_f32_e32 v54, v53
	v_mul_f32_e32 v53, 0xbfb8aa3b, v49
	v_exp_f32_e32 v55, v53
	v_rcp_f32_e32 v53, v51
	v_add_f32_e32 v51, 1.0, v54
	v_rcp_f32_e32 v54, v51
	v_add_f32_e32 v51, 1.0, v55
	v_rcp_f32_e32 v55, v51
	v_pk_mul_f32 v[46:47], v[46:47], v[52:53]
	v_pk_mul_f32 v[42:43], v[42:43], v[50:51] op_sel_hi:[1,0]
	v_pk_mul_f32 v[38:39], v[38:39], v[46:47]
	v_pk_mul_f32 v[46:47], v[48:49], v[54:55]
	v_mul_f32_e32 v48, 0xbfb8aa3b, v42
	v_exp_f32_e32 v48, v48
	v_pk_mul_f32 v[40:41], v[40:41], v[50:51] op_sel_hi:[1,0]
	v_pk_mul_f32 v[44:45], v[44:45], v[50:51] op_sel_hi:[1,0]
	v_pk_mul_f32 v[40:41], v[40:41], v[46:47]
	v_mul_f32_e32 v46, 0xbfb8aa3b, v43
	v_exp_f32_e32 v47, v46
	v_add_f32_e32 v46, 1.0, v48
	v_mul_f32_e32 v48, 0xbfb8aa3b, v44
	v_mul_f32_e32 v49, 0xbfb8aa3b, v45
	v_exp_f32_e32 v48, v48
	v_exp_f32_e32 v49, v49
	v_add_f32_e32 v47, 1.0, v47
	v_rcp_f32_e32 v46, v46
	v_rcp_f32_e32 v47, v47
	v_add_f32_e32 v48, 1.0, v48
	v_add_f32_e32 v49, 1.0, v49
	v_rcp_f32_e32 v48, v48
	v_rcp_f32_e32 v49, v49
	v_pk_mul_f32 v[34:35], v[34:35], v[50:51] op_sel_hi:[1,0]
	v_pk_mul_f32 v[42:43], v[42:43], v[46:47]
	s_nop 0
	v_pk_mul_f32 v[42:43], v[34:35], v[42:43]
	v_pk_mul_f32 v[34:35], v[36:37], v[50:51] op_sel_hi:[1,0]
	v_pk_mul_f32 v[36:37], v[44:45], v[48:49]
	s_nop 0
	v_pk_mul_f32 v[44:45], v[34:35], v[36:37]
	v_cvt_pk_bf16_f32 v34, v38, v39
	ds_read2_b32 v[38:39], v74 offset0:160 offset1:176
	v_cvt_pk_bf16_f32 v35, v40, v41
	v_mad_i64_i32 v[40:41], s[20:21], v56, s13, v[110:111]
	v_cvt_pk_bf16_f32 v36, v42, v43
	v_cvt_pk_bf16_f32 v37, v44, v45
	v_lshl_add_u64 v[40:41], v[40:41], 0, v[112:113]
	s_waitcnt lgkmcnt(0)
	v_pk_mul_f32 v[30:31], v[30:31], v[38:39] op_sel_hi:[1,0]
	global_store_dwordx4 v[40:41], v[34:37], off sc1
	v_pk_mul_f32 v[32:33], v[32:33], v[38:39] op_sel_hi:[1,0]
	v_pk_mul_f32 v[22:23], v[22:23], v[38:39] op_sel_hi:[1,0]
	v_mul_f32_e32 v34, 0xbfb8aa3b, v30
	v_mul_f32_e32 v35, 0xbfb8aa3b, v31
	v_exp_f32_e32 v34, v34
	v_exp_f32_e32 v35, v35
	v_mul_f32_e32 v36, 0xbfb8aa3b, v32
	v_mul_f32_e32 v37, 0xbfb8aa3b, v33
	v_exp_f32_e32 v36, v36
	v_exp_f32_e32 v37, v37
	v_add_f32_e32 v34, 1.0, v34
	v_add_f32_e32 v35, 1.0, v35
	v_rcp_f32_e32 v34, v34
	v_rcp_f32_e32 v35, v35
	v_add_f32_e32 v36, 1.0, v36
	v_add_f32_e32 v37, 1.0, v37
	v_rcp_f32_e32 v36, v36
	v_rcp_f32_e32 v37, v37
	v_pk_mul_f32 v[30:31], v[30:31], v[34:35]
	v_pk_mul_f32 v[26:27], v[26:27], v[38:39] op_sel_hi:[1,0]
	v_pk_mul_f32 v[22:23], v[22:23], v[30:31]
	v_pk_mul_f32 v[30:31], v[32:33], v[36:37]
	v_mul_f32_e32 v32, 0xbfb8aa3b, v26
	v_exp_f32_e32 v32, v32
	v_pk_mul_f32 v[24:25], v[24:25], v[38:39] op_sel_hi:[1,0]
	v_pk_mul_f32 v[28:29], v[28:29], v[38:39] op_sel_hi:[1,0]
	v_pk_mul_f32 v[24:25], v[24:25], v[30:31]
	v_mul_f32_e32 v30, 0xbfb8aa3b, v27
	v_exp_f32_e32 v31, v30
	v_add_f32_e32 v30, 1.0, v32
	v_mul_f32_e32 v32, 0xbfb8aa3b, v28
	v_mul_f32_e32 v33, 0xbfb8aa3b, v29
	v_exp_f32_e32 v32, v32
	v_exp_f32_e32 v33, v33
	v_add_f32_e32 v31, 1.0, v31
	v_rcp_f32_e32 v30, v30
	v_rcp_f32_e32 v31, v31
	v_add_f32_e32 v32, 1.0, v32
	v_add_f32_e32 v33, 1.0, v33
	v_rcp_f32_e32 v32, v32
	v_rcp_f32_e32 v33, v33
	v_pk_mul_f32 v[18:19], v[18:19], v[38:39] op_sel_hi:[1,0]
	v_pk_mul_f32 v[26:27], v[26:27], v[30:31]
	v_add_u32_e32 v40, 0xa0, v149
	v_pk_mul_f32 v[26:27], v[18:19], v[26:27]
	v_pk_mul_f32 v[18:19], v[20:21], v[38:39] op_sel_hi:[1,0]
	v_pk_mul_f32 v[20:21], v[28:29], v[32:33]
	s_nop 0
	v_pk_mul_f32 v[28:29], v[18:19], v[20:21]
	v_cvt_pk_bf16_f32 v18, v22, v23
	v_mad_i64_i32 v[22:23], s[20:21], v40, s13, v[110:111]
	v_cvt_pk_bf16_f32 v19, v24, v25
	v_cvt_pk_bf16_f32 v20, v26, v27
	v_cvt_pk_bf16_f32 v21, v28, v29
	v_lshl_add_u64 v[22:23], v[22:23], 0, v[112:113]
	global_store_dwordx4 v[22:23], v[18:21], off sc1
	v_add_u32_e32 v24, 0xb0, v149
	s_nop 0
	v_mov_b32_e32 v18, v39
	v_pk_mul_f32 v[14:15], v[14:15], v[18:19] op_sel_hi:[1,0]
	s_nop 0
	v_mul_f32_e32 v19, 0xbfb8aa3b, v14
	v_exp_f32_e32 v19, v19
	v_mul_f32_e32 v20, 0xbfb8aa3b, v15
	v_exp_f32_e32 v21, v20
	v_add_f32_e32 v19, 1.0, v19
	v_rcp_f32_e32 v20, v19
	v_pk_mul_f32 v[6:7], v[6:7], v[18:19] op_sel_hi:[1,0]
	v_add_f32_e32 v19, 1.0, v21
	v_pk_mul_f32 v[16:17], v[16:17], v[18:19] op_sel_hi:[1,0]
	s_nop 0
	v_mul_f32_e32 v21, 0xbfb8aa3b, v16
	v_exp_f32_e32 v22, v21
	v_mul_f32_e32 v21, 0xbfb8aa3b, v17
	v_exp_f32_e32 v23, v21
	v_rcp_f32_e32 v21, v19
	v_add_f32_e32 v19, 1.0, v22
	v_rcp_f32_e32 v22, v19
	v_add_f32_e32 v19, 1.0, v23
	v_rcp_f32_e32 v23, v19
	v_pk_mul_f32 v[14:15], v[14:15], v[20:21]
	v_pk_mul_f32 v[10:11], v[10:11], v[18:19] op_sel_hi:[1,0]
	v_pk_mul_f32 v[6:7], v[6:7], v[14:15]
	v_pk_mul_f32 v[14:15], v[16:17], v[22:23]
	v_mul_f32_e32 v16, 0xbfb8aa3b, v10
	v_exp_f32_e32 v16, v16
	v_pk_mul_f32 v[8:9], v[8:9], v[18:19] op_sel_hi:[1,0]
	v_pk_mul_f32 v[12:13], v[12:13], v[18:19] op_sel_hi:[1,0]
	v_pk_mul_f32 v[8:9], v[8:9], v[14:15]
	v_mul_f32_e32 v14, 0xbfb8aa3b, v11
	v_exp_f32_e32 v15, v14
	v_add_f32_e32 v14, 1.0, v16
	v_mul_f32_e32 v16, 0xbfb8aa3b, v12
	v_mul_f32_e32 v17, 0xbfb8aa3b, v13
	v_exp_f32_e32 v16, v16
	v_exp_f32_e32 v17, v17
	v_add_f32_e32 v15, 1.0, v15
	v_rcp_f32_e32 v14, v14
	v_rcp_f32_e32 v15, v15
	v_add_f32_e32 v16, 1.0, v16
	v_add_f32_e32 v17, 1.0, v17
	v_rcp_f32_e32 v16, v16
	v_rcp_f32_e32 v17, v17
	v_pk_mul_f32 v[2:3], v[2:3], v[18:19] op_sel_hi:[1,0]
	v_pk_mul_f32 v[10:11], v[10:11], v[14:15]
	s_nop 0
	v_pk_mul_f32 v[10:11], v[2:3], v[10:11]
	v_pk_mul_f32 v[2:3], v[4:5], v[18:19] op_sel_hi:[1,0]
	v_pk_mul_f32 v[4:5], v[12:13], v[16:17]
	s_nop 0
	v_pk_mul_f32 v[12:13], v[2:3], v[4:5]
	v_cvt_pk_bf16_f32 v2, v6, v7
	v_mad_i64_i32 v[6:7], s[20:21], v24, s13, v[110:111]
	v_cvt_pk_bf16_f32 v3, v8, v9
	v_cvt_pk_bf16_f32 v4, v10, v11
	v_cvt_pk_bf16_f32 v5, v12, v13
	v_lshl_add_u64 v[6:7], v[6:7], 0, v[112:113]
	global_store_dwordx4 v[6:7], v[2:5], off sc1
	s_cbranch_vccnz .LBB0_1350
	s_andn2_b64 vcc, exec, s[2:3]
	s_cbranch_vccnz .LBB0_1349
	s_barrier
	s_branch .LBB0_1349
